# MFMA/VALU interleave in the attention loop: the row-max chain of the next tile's softmax is woven into the gaps of the 16 P.V MFMAs instead of running after them
# speedup vs baseline: 1.0139x; 1.0139x over previous
; __device__ __forceinline__ void mask_tile(f32x16& p0, f32x16& p1, int dq, unsigned W) {
;     const float NEG = -__builtin_inff();
; #pragma unroll
;     for (int r = 0; r < 16; ++r) {
;         const int c = (r & 3) + 8 * (r >> 2);
;         if ((unsigned)(dq - c) >= W) p0[r] = NEG;
;         if ((unsigned)(dq - c - 32) >= W) p1[r] = NEG;
;     }
; }
.LBB0_805:
	s_add_i32 s69, s14, 63
	s_lshl_b64 s[10:11], s[46:47], 8
	s_add_u32 s48, s34, s10
	s_addc_u32 s49, s35, s11
	s_add_u32 s10, s36, s10
	s_addc_u32 s11, s37, s11
	v_lshl_add_u64 v[112:113], s[10:11], 0, v[194:195]
	v_add_co_u32_e32 v114, vcc, s59, v112
	s_nop 1
	v_addc_co_u32_e32 v115, vcc, 0, v113, vcc
	flat_load_dwordx4 v[160:163], v[112:113]
	flat_load_dwordx4 v[164:167], v[114:115]
	v_lshl_add_u64 v[112:113], s[48:49], 0, v[194:195]
	v_add_co_u32_e32 v114, vcc, s59, v112
	s_nop 1
	v_addc_co_u32_e32 v115, vcc, 0, v113, vcc
	flat_load_dwordx4 v[168:171], v[112:113]
	flat_load_dwordx4 v[172:175], v[114:115]
	s_cmp_le_i32 s69, s31
	s_cselect_b64 s[10:11], -1, 0
	s_cmp_gt_i32 s14, s67
	s_cselect_b64 s[48:49], -1, 0
	s_and_b64 s[10:11], s[10:11], s[48:49]
	s_and_b64 vcc, exec, s[10:11]
	s_nop 3
	s_cbranch_vccnz .LBB0_807
	v_subrev_u32_e32 v252, 64, v224
	v_cmp_gt_u32_e32 vcc, s61, v252
	v_add_u32_e32 v252, 0xffffefa0, v224
	s_nop 0
	v_cndmask_b32_e32 v84, v203, v84, vcc
	v_cmp_lt_u32_e32 vcc, s62, v252
	v_add_u32_e32 v252, 0xffffefbf, v224
	s_nop 0
	v_cndmask_b32_e32 v68, v203, v68, vcc
	v_cmp_lt_u32_e32 vcc, s62, v252
	v_add_u32_e32 v252, 0xffffef9f, v224
	s_nop 0
	v_cndmask_b32_e32 v85, v203, v85, vcc
	v_cmp_lt_u32_e32 vcc, s62, v252
	v_add_u32_e32 v252, 0xffffefbe, v224
	s_nop 0
	v_cndmask_b32_e32 v69, v203, v69, vcc
	v_cmp_lt_u32_e32 vcc, s62, v252
	v_add_u32_e32 v252, 0xffffef9e, v224
	s_nop 0
	v_cndmask_b32_e32 v86, v203, v86, vcc
	v_cmp_lt_u32_e32 vcc, s62, v252
	v_add_u32_e32 v252, 0xffffefbd, v224
	s_nop 0
	v_cndmask_b32_e32 v70, v203, v70, vcc
	v_cmp_lt_u32_e32 vcc, s62, v252
	v_add_u32_e32 v252, 0xffffef9d, v224
	s_nop 0
	v_cndmask_b32_e32 v87, v203, v87, vcc
	v_cmp_lt_u32_e32 vcc, s62, v252
	v_add_u32_e32 v252, 0xffffefb8, v224
	s_nop 0
	v_cndmask_b32_e32 v71, v203, v71, vcc
	v_cmp_lt_u32_e32 vcc, s62, v252
	v_add_u32_e32 v252, 0xffffef98, v224
	s_nop 0
	v_cndmask_b32_e32 v88, v203, v88, vcc
	v_cmp_lt_u32_e32 vcc, s62, v252
	v_add_u32_e32 v252, 0xffffefb7, v224
	s_nop 0
	v_cndmask_b32_e32 v72, v203, v72, vcc
	v_cmp_lt_u32_e32 vcc, s62, v252
	v_add_u32_e32 v252, 0xffffef97, v224
	s_nop 0
	v_cndmask_b32_e32 v89, v203, v89, vcc
	v_cmp_lt_u32_e32 vcc, s62, v252
	v_add_u32_e32 v252, 0xffffefb6, v224
	s_nop 0
	v_cndmask_b32_e32 v73, v203, v73, vcc
	v_cmp_lt_u32_e32 vcc, s62, v252
	v_add_u32_e32 v252, 0xffffef96, v224
	s_nop 0
	v_cndmask_b32_e32 v90, v203, v90, vcc
	v_cmp_lt_u32_e32 vcc, s62, v252
	v_add_u32_e32 v252, 0xffffefb5, v224
	s_nop 0
	v_cndmask_b32_e32 v74, v203, v74, vcc
	v_cmp_lt_u32_e32 vcc, s62, v252
	v_add_u32_e32 v252, 0xffffef95, v224
	s_nop 0
	v_cndmask_b32_e32 v91, v203, v91, vcc
	v_cmp_lt_u32_e32 vcc, s62, v252
	v_add_u32_e32 v252, 0xffffefb0, v224
	s_nop 0
	v_cndmask_b32_e32 v75, v203, v75, vcc
	v_cmp_lt_u32_e32 vcc, s62, v252
	v_add_u32_e32 v252, 0xffffef90, v224
	s_nop 0
	v_cndmask_b32_e32 v92, v203, v92, vcc
	v_cmp_lt_u32_e32 vcc, s62, v252
	v_add_u32_e32 v252, 0xffffefaf, v224
	s_nop 0
	v_cndmask_b32_e32 v76, v203, v76, vcc
	v_cmp_lt_u32_e32 vcc, s62, v252
	v_add_u32_e32 v252, 0xffffef8f, v224
	s_nop 0
	v_cndmask_b32_e32 v93, v203, v93, vcc
	v_cmp_lt_u32_e32 vcc, s62, v252
	v_add_u32_e32 v252, 0xffffefae, v224
	s_nop 0
	v_cndmask_b32_e32 v77, v203, v77, vcc
	v_cmp_lt_u32_e32 vcc, s62, v252
	v_add_u32_e32 v252, 0xffffef8e, v224
	s_nop 0
	v_cndmask_b32_e32 v94, v203, v94, vcc
	v_cmp_lt_u32_e32 vcc, s62, v252
	v_add_u32_e32 v252, 0xffffefad, v224
	s_nop 0
	v_cndmask_b32_e32 v78, v203, v78, vcc
	v_cmp_lt_u32_e32 vcc, s62, v252
	v_add_u32_e32 v252, 0xffffef8d, v224
	s_nop 0
	v_cndmask_b32_e32 v95, v203, v95, vcc
	v_cmp_lt_u32_e32 vcc, s62, v252
	v_add_u32_e32 v252, 0xffffefa8, v224
	s_nop 0
	v_cndmask_b32_e32 v79, v203, v79, vcc
	v_cmp_lt_u32_e32 vcc, s62, v252
	v_add_u32_e32 v252, 0xffffef88, v224
	s_nop 0
	v_cndmask_b32_e32 v96, v203, v96, vcc
	v_cmp_lt_u32_e32 vcc, s62, v252
	v_add_u32_e32 v252, 0xffffefa7, v224
	s_nop 0
	v_cndmask_b32_e32 v80, v203, v80, vcc
	v_cmp_lt_u32_e32 vcc, s62, v252
	v_add_u32_e32 v252, 0xffffef87, v224
	s_nop 0
	v_cndmask_b32_e32 v97, v203, v97, vcc
	v_cmp_lt_u32_e32 vcc, s62, v252
	v_add_u32_e32 v252, 0xffffefa6, v224
	s_nop 0
	v_cndmask_b32_e32 v81, v203, v81, vcc
	v_cmp_lt_u32_e32 vcc, s62, v252
	v_add_u32_e32 v252, 0xffffef86, v224
	s_nop 0
	v_cndmask_b32_e32 v98, v203, v98, vcc
	v_cmp_lt_u32_e32 vcc, s62, v252
	v_add_u32_e32 v252, 0xffffefa5, v224
	s_nop 0
	v_cndmask_b32_e32 v82, v203, v82, vcc
	v_cmp_lt_u32_e32 vcc, s62, v252
	v_add_u32_e32 v252, 0xffffef85, v224
	s_nop 0
	v_cndmask_b32_e32 v99, v203, v99, vcc
	v_cmp_lt_u32_e32 vcc, s62, v252
	s_nop 1
	v_cndmask_b32_e32 v83, v203, v83, vcc
;     __device__ __forceinline__ static float act(float g, float u) { return g * __builtin_amdgcn_rcpf(1.0f + __builtin_amdgcn_exp2f(g * -1.4426950408889634f)) * u; }
; __device__ __forceinline__ void partialSM(f32x16& p0, f32x16& p1, float& m_reg, float& mn, float& alpha) {
;     float pmax = p0[0]; for (int r = 1; r < 16; ++r) pmax = fmaxf(pmax, p0[r]); for (int r = 0; r < 16; ++r) pmax = fmaxf(pmax, p1[r]);
;     { auto rr = __builtin_amdgcn_permlane32_swap(__float_as_uint(pmax), __float_as_uint(pmax), false, false);
;       pmax = fmaxf(__uint_as_float(rr[0]), __uint_as_float(rr[1])); }
;     constexpr float C2 = 1.4426950408889634f * SCALE;
;     if (__builtin_expect(__all((pmax - m_reg) * SCALE <= THR), 1)) { mn = m_reg; alpha = 1.f; }
; template <int VB, bool SK>
; __device__ __forceinline__ void pv_tile(f32x16* o, int vb0, bf16x8 pa0, bf16x8 pa1, bf16x8 pa2, bf16x8 pa3, bool act) {
;     if (SK && !act) return;
;     ...
;     PV_D0(0); PV_D0(1); PV_D0(2); PV_D0(3);
.LBB0_807:
	ds_read_b64_tr_b16 v[112:113], v213 offset:0
	ds_read_b64_tr_b16 v[114:115], v213 offset:0x800
	ds_read_b64_tr_b16 v[116:117], v213 offset:0x1000
	ds_read_b64_tr_b16 v[118:119], v213 offset:0x1800
	ds_read_b64_tr_b16 v[120:121], v213 offset:0x2000
	ds_read_b64_tr_b16 v[122:123], v213 offset:0x2800
	ds_read_b64_tr_b16 v[124:125], v213 offset:0x3000
	ds_read_b64_tr_b16 v[126:127], v213 offset:0x3800
	s_waitcnt lgkmcnt(0)
	s_nop 0
	v_mfma_f32_32x32x16_bf16 v[32:47], v[64:67], v[112:115], v[32:47]
	v_max_f32_e32 v252, v85, v85
	v_max_f32_e32 v253, v84, v84
	ds_read_b64_tr_b16 v[112:113], v213 offset:0x200
	ds_read_b64_tr_b16 v[114:115], v213 offset:0xa00
	v_mfma_f32_32x32x16_bf16 v[32:47], v[100:103], v[116:119], v[32:47]
	v_max_f32_e32 v252, v253, v252
	v_max3_f32 v252, v252, v86, v87
	ds_read_b64_tr_b16 v[116:117], v213 offset:0x1200
	ds_read_b64_tr_b16 v[118:119], v213 offset:0x1a00
	v_mfma_f32_32x32x16_bf16 v[32:47], v[108:111], v[120:123], v[32:47]
	v_max3_f32 v252, v252, v88, v89
	v_max3_f32 v252, v252, v90, v91
	ds_read_b64_tr_b16 v[120:121], v213 offset:0x2200
	ds_read_b64_tr_b16 v[122:123], v213 offset:0x2a00
	ds_read_b64_tr_b16 v[178:179], v213 offset:0x3200
	ds_read_b64_tr_b16 v[180:181], v213 offset:0x3a00
	s_waitcnt lgkmcnt(0)
	v_mfma_f32_32x32x16_bf16 v[32:47], v[104:107], v[124:127], v[32:47]
	v_max3_f32 v252, v252, v92, v93
	v_max3_f32 v252, v252, v94, v95
	v_mfma_f32_32x32x16_bf16 v[48:63], v[64:67], v[112:115], v[48:63]
	v_max3_f32 v252, v252, v96, v97
	v_max3_f32 v252, v252, v98, v99
	ds_read_b64_tr_b16 v[112:113], v213 offset:0x400
	ds_read_b64_tr_b16 v[114:115], v213 offset:0xc00
	v_mfma_f32_32x32x16_bf16 v[48:63], v[100:103], v[116:119], v[48:63]
	v_max3_f32 v252, v252, v68, v69
	v_max3_f32 v252, v252, v70, v71
	ds_read_b64_tr_b16 v[116:117], v213 offset:0x1400
	ds_read_b64_tr_b16 v[118:119], v213 offset:0x1c00
	v_mfma_f32_32x32x16_bf16 v[48:63], v[108:111], v[120:123], v[48:63]
	v_max3_f32 v252, v252, v72, v73
	v_max3_f32 v252, v252, v74, v75
	ds_read_b64_tr_b16 v[120:121], v213 offset:0x2400
	ds_read_b64_tr_b16 v[122:123], v213 offset:0x2c00
	ds_read_b64_tr_b16 v[124:125], v213 offset:0x3400
	ds_read_b64_tr_b16 v[126:127], v213 offset:0x3c00
	s_waitcnt lgkmcnt(0)
	v_mfma_f32_32x32x16_bf16 v[48:63], v[104:107], v[178:181], v[48:63]
	v_max3_f32 v252, v252, v76, v77
	v_max3_f32 v252, v252, v78, v79
	v_mfma_f32_32x32x16_bf16 v[16:31], v[64:67], v[112:115], v[16:31]
	v_max3_f32 v252, v252, v80, v81
	v_max3_f32 v252, v252, v82, v83
	ds_read_b64_tr_b16 v[112:113], v213 offset:0x600
	ds_read_b64_tr_b16 v[114:115], v213 offset:0xe00
	v_mfma_f32_32x32x16_bf16 v[16:31], v[100:103], v[116:119], v[16:31]
	v_mov_b32_e32 v253, v252
	s_nop 1
	ds_read_b64_tr_b16 v[116:117], v213 offset:0x1600
	ds_read_b64_tr_b16 v[118:119], v213 offset:0x1e00
	v_mfma_f32_32x32x16_bf16 v[16:31], v[108:111], v[120:123], v[16:31]
	v_permlane32_swap_b32_e32 v252, v253
	v_max_f32_e32 v253, v253, v253
	ds_read_b64_tr_b16 v[120:121], v213 offset:0x2600
	ds_read_b64_tr_b16 v[122:123], v213 offset:0x2e00
	ds_read_b64_tr_b16 v[178:179], v213 offset:0x3600
	ds_read_b64_tr_b16 v[180:181], v213 offset:0x3e00
	s_waitcnt lgkmcnt(0)
	v_mfma_f32_32x32x16_bf16 v[16:31], v[104:107], v[124:127], v[16:31]
	v_max_f32_e32 v252, v252, v252
	v_max_f32_e32 v252, v252, v253
	v_mfma_f32_32x32x16_bf16 v[0:15], v[64:67], v[112:115], v[0:15]
	v_sub_f32_e32 v253, v252, v176
	v_mul_f32_e32 v253, 0x3db504f3, v253
	v_mfma_f32_32x32x16_bf16 v[0:15], v[100:103], v[116:119], v[0:15]
	v_cmp_ge_f32_e32 vcc, s63, v253
	v_mfma_f32_32x32x16_bf16 v[0:15], v[108:111], v[120:123], v[0:15]
	v_mfma_f32_32x32x16_bf16 v[0:15], v[104:107], v[178:181], v[0:15]
	v_mov_b32_e32 v64, v252
	s_waitcnt lgkmcnt(0)
	s_barrier
	s_waitcnt vmcnt(0)
	s_cmp_eq_u64 vcc, exec
	s_cselect_b64 s[10:11], -1, 0
	s_and_b64 vcc, exec, s[6:7]
	s_waitcnt vmcnt(0)
	ds_write_b128 v199, v[160:163]
	ds_write_b128 v215, v[164:167]
	s_cbranch_vccnz .LBB0_809
	v_xor_b32_e32 v65, 0x80000000, v202
	ds_write_b32 v212, v65

; __device__ __forceinline__ void mask_tile(f32x16& p0, f32x16& p1, int dq, unsigned W) {
;     const float NEG = -__builtin_inff();
; #pragma unroll
;     for (int r = 0; r < 16; ++r) {
;         const int c = (r & 3) + 8 * (r >> 2);
;         if ((unsigned)(dq - c) >= W) p0[r] = NEG;
;         if ((unsigned)(dq - c - 32) >= W) p1[r] = NEG;
;     }
; }
.LBB0_817:
	s_add_i32 s10, s14, -1
	s_cmp_le_i32 s10, s31
	s_cselect_b64 s[10:11], -1, 0
	s_cmp_gt_i32 s46, s67
	s_cselect_b64 s[46:47], -1, 0
	s_and_b64 s[10:11], s[10:11], s[46:47]
	s_and_b64 vcc, exec, s[10:11]
	s_nop 3
	s_cbranch_vccnz .LBB0_819
	v_cmp_gt_u32_e32 vcc, s61, v224
	v_add_u32_e32 v252, 0xffffefe0, v224
	s_nop 0
	v_cndmask_b32_e32 v112, v203, v112, vcc
	v_cmp_lt_u32_e32 vcc, s62, v252
	v_add_u32_e32 v252, 0xffffefff, v224
	s_nop 0
	v_cndmask_b32_e32 v96, v203, v96, vcc
	v_cmp_lt_u32_e32 vcc, s62, v252
	v_add_u32_e32 v252, 0xffffefdf, v224
	s_nop 0
	v_cndmask_b32_e32 v113, v203, v113, vcc
	v_cmp_lt_u32_e32 vcc, s62, v252
	v_add_u32_e32 v252, 0xffffeffe, v224
	s_nop 0
	v_cndmask_b32_e32 v97, v203, v97, vcc
	v_cmp_lt_u32_e32 vcc, s62, v252
	v_add_u32_e32 v252, 0xffffefde, v224
	s_nop 0
	v_cndmask_b32_e32 v114, v203, v114, vcc
	v_cmp_lt_u32_e32 vcc, s62, v252
	v_add_u32_e32 v252, 0xffffeffd, v224
	s_nop 0
	v_cndmask_b32_e32 v98, v203, v98, vcc
	v_cmp_lt_u32_e32 vcc, s62, v252
	v_add_u32_e32 v252, 0xffffefdd, v224
	s_nop 0
	v_cndmask_b32_e32 v115, v203, v115, vcc
	v_cmp_lt_u32_e32 vcc, s62, v252
	v_add_u32_e32 v252, 0xffffeff8, v224
	s_nop 0
	v_cndmask_b32_e32 v99, v203, v99, vcc
	v_cmp_lt_u32_e32 vcc, s62, v252
	v_add_u32_e32 v252, 0xffffefd8, v224
	s_nop 0
	v_cndmask_b32_e32 v116, v203, v116, vcc
	v_cmp_lt_u32_e32 vcc, s62, v252
	v_add_u32_e32 v252, 0xffffeff7, v224
	s_nop 0
	v_cndmask_b32_e32 v100, v203, v100, vcc
	v_cmp_lt_u32_e32 vcc, s62, v252
	v_add_u32_e32 v252, 0xffffefd7, v224
	s_nop 0
	v_cndmask_b32_e32 v117, v203, v117, vcc
	v_cmp_lt_u32_e32 vcc, s62, v252
	v_add_u32_e32 v252, 0xffffeff6, v224
	s_nop 0
	v_cndmask_b32_e32 v101, v203, v101, vcc
	v_cmp_lt_u32_e32 vcc, s62, v252
	v_add_u32_e32 v252, 0xffffefd6, v224
	s_nop 0
	v_cndmask_b32_e32 v118, v203, v118, vcc
	v_cmp_lt_u32_e32 vcc, s62, v252
	v_add_u32_e32 v252, 0xffffeff5, v224
	s_nop 0
	v_cndmask_b32_e32 v102, v203, v102, vcc
	v_cmp_lt_u32_e32 vcc, s62, v252
	v_add_u32_e32 v252, 0xffffefd5, v224
	s_nop 0
	v_cndmask_b32_e32 v119, v203, v119, vcc
	v_cmp_lt_u32_e32 vcc, s62, v252
	v_add_u32_e32 v252, 0xffffeff0, v224
	s_nop 0
	v_cndmask_b32_e32 v103, v203, v103, vcc
	v_cmp_lt_u32_e32 vcc, s62, v252
	v_add_u32_e32 v252, 0xffffefd0, v224
	s_nop 0
	v_cndmask_b32_e32 v120, v203, v120, vcc
	v_cmp_lt_u32_e32 vcc, s62, v252
	v_add_u32_e32 v252, 0xffffefef, v224
	s_nop 0
	v_cndmask_b32_e32 v104, v203, v104, vcc
	v_cmp_lt_u32_e32 vcc, s62, v252
	v_add_u32_e32 v252, 0xffffefcf, v224
	s_nop 0
	v_cndmask_b32_e32 v121, v203, v121, vcc
	v_cmp_lt_u32_e32 vcc, s62, v252
	v_add_u32_e32 v252, 0xffffefee, v224
	s_nop 0
	v_cndmask_b32_e32 v105, v203, v105, vcc
	v_cmp_lt_u32_e32 vcc, s62, v252
	v_add_u32_e32 v252, 0xffffefce, v224
	s_nop 0
	v_cndmask_b32_e32 v122, v203, v122, vcc
	v_cmp_lt_u32_e32 vcc, s62, v252
	v_add_u32_e32 v252, 0xffffefed, v224
	s_nop 0
	v_cndmask_b32_e32 v106, v203, v106, vcc
	v_cmp_lt_u32_e32 vcc, s62, v252
	v_add_u32_e32 v252, 0xffffefcd, v224
	s_nop 0
	v_cndmask_b32_e32 v123, v203, v123, vcc
	v_cmp_lt_u32_e32 vcc, s62, v252
	v_add_u32_e32 v252, 0xffffefe8, v224
	s_nop 0
	v_cndmask_b32_e32 v107, v203, v107, vcc
	v_cmp_lt_u32_e32 vcc, s62, v252
	v_add_u32_e32 v252, 0xffffefc8, v224
	s_nop 0
	v_cndmask_b32_e32 v124, v203, v124, vcc
	v_cmp_lt_u32_e32 vcc, s62, v252
	v_add_u32_e32 v252, 0xffffefe7, v224
	s_nop 0
	v_cndmask_b32_e32 v108, v203, v108, vcc
	v_cmp_lt_u32_e32 vcc, s62, v252
	v_add_u32_e32 v252, 0xffffefc7, v224
	s_nop 0
	v_cndmask_b32_e32 v125, v203, v125, vcc
	v_cmp_lt_u32_e32 vcc, s62, v252
	v_add_u32_e32 v252, 0xffffefe6, v224
	s_nop 0
	v_cndmask_b32_e32 v109, v203, v109, vcc
	v_cmp_lt_u32_e32 vcc, s62, v252
	v_add_u32_e32 v252, 0xffffefc6, v224
	s_nop 0
	v_cndmask_b32_e32 v126, v203, v126, vcc
	v_cmp_lt_u32_e32 vcc, s62, v252
	v_add_u32_e32 v252, 0xffffefe5, v224
	s_nop 0
	v_cndmask_b32_e32 v110, v203, v110, vcc
	v_cmp_lt_u32_e32 vcc, s62, v252
	v_add_u32_e32 v252, 0xffffefc5, v224
	s_nop 0
	v_cndmask_b32_e32 v127, v203, v127, vcc
	v_cmp_lt_u32_e32 vcc, s62, v252
	s_nop 1
	v_cndmask_b32_e32 v111, v203, v111, vcc
;     __device__ __forceinline__ static float act(float g, float u) { return g * __builtin_amdgcn_rcpf(1.0f + __builtin_amdgcn_exp2f(g * -1.4426950408889634f)) * u; }
; __device__ __forceinline__ void partialSM(f32x16& p0, f32x16& p1, float& m_reg, float& mn, float& alpha) {
;     float pmax = p0[0]; for (int r = 1; r < 16; ++r) pmax = fmaxf(pmax, p0[r]); for (int r = 0; r < 16; ++r) pmax = fmaxf(pmax, p1[r]);
;     { auto rr = __builtin_amdgcn_permlane32_swap(__float_as_uint(pmax), __float_as_uint(pmax), false, false);
;       pmax = fmaxf(__uint_as_float(rr[0]), __uint_as_float(rr[1])); }
;     constexpr float C2 = 1.4426950408889634f * SCALE;
;     if (__builtin_expect(__all((pmax - m_reg) * SCALE <= THR), 1)) { mn = m_reg; alpha = 1.f; }
; template <int VB, bool SK>
; __device__ __forceinline__ void pv_tile(f32x16* o, int vb0, bf16x8 pa0, bf16x8 pa1, bf16x8 pa2, bf16x8 pa3, bool act) {
;     if (SK && !act) return;
;     ...
;     PV_D0(0); PV_D0(1); PV_D0(2); PV_D0(3);
.LBB0_819:
	ds_read_b64_tr_b16 v[232:233], v213 offset:0x4000
	ds_read_b64_tr_b16 v[234:235], v213 offset:0x4800
	ds_read_b64_tr_b16 v[236:237], v213 offset:0x5000
	ds_read_b64_tr_b16 v[238:239], v213 offset:0x5800
	ds_read_b64_tr_b16 v[240:241], v213 offset:0x6000
	ds_read_b64_tr_b16 v[242:243], v213 offset:0x6800
	ds_read_b64_tr_b16 v[244:245], v213 offset:0x7000
	ds_read_b64_tr_b16 v[246:247], v213 offset:0x7800
	s_waitcnt lgkmcnt(0)
	v_mfma_f32_32x32x16_bf16 v[32:47], v[176:179], v[232:235], v[32:47]
	v_max_f32_e32 v252, v113, v113
	v_max_f32_e32 v253, v112, v112
	ds_read_b64_tr_b16 v[232:233], v213 offset:0x4200
	ds_read_b64_tr_b16 v[234:235], v213 offset:0x4a00
	v_mfma_f32_32x32x16_bf16 v[32:47], v[180:183], v[236:239], v[32:47]
	v_max_f32_e32 v252, v253, v252
	v_max3_f32 v252, v252, v114, v115
	ds_read_b64_tr_b16 v[236:237], v213 offset:0x5200
	ds_read_b64_tr_b16 v[238:239], v213 offset:0x5a00
	v_mfma_f32_32x32x16_bf16 v[32:47], v[184:187], v[240:243], v[32:47]
	v_max3_f32 v252, v252, v116, v117
	v_max3_f32 v252, v252, v118, v119
	ds_read_b64_tr_b16 v[240:241], v213 offset:0x6200
	ds_read_b64_tr_b16 v[242:243], v213 offset:0x6a00
	ds_read_b64_tr_b16 v[248:249], v213 offset:0x7200
	ds_read_b64_tr_b16 v[250:251], v213 offset:0x7a00
	s_waitcnt lgkmcnt(0)
	v_mfma_f32_32x32x16_bf16 v[32:47], v[188:191], v[244:247], v[32:47]
	v_max3_f32 v252, v252, v120, v121
	v_max3_f32 v252, v252, v122, v123
	v_mfma_f32_32x32x16_bf16 v[48:63], v[176:179], v[232:235], v[48:63]
	v_max3_f32 v252, v252, v124, v125
	v_max3_f32 v252, v252, v126, v127
	ds_read_b64_tr_b16 v[232:233], v213 offset:0x4400
	ds_read_b64_tr_b16 v[234:235], v213 offset:0x4c00
	v_mfma_f32_32x32x16_bf16 v[48:63], v[180:183], v[236:239], v[48:63]
	v_max3_f32 v252, v252, v96, v97
	v_max3_f32 v252, v252, v98, v99
	ds_read_b64_tr_b16 v[236:237], v213 offset:0x5400
	ds_read_b64_tr_b16 v[238:239], v213 offset:0x5c00
	v_mfma_f32_32x32x16_bf16 v[48:63], v[184:187], v[240:243], v[48:63]
	v_max3_f32 v252, v252, v100, v101
	v_max3_f32 v252, v252, v102, v103
	ds_read_b64_tr_b16 v[240:241], v213 offset:0x6400
	ds_read_b64_tr_b16 v[242:243], v213 offset:0x6c00
	ds_read_b64_tr_b16 v[244:245], v213 offset:0x7400
	ds_read_b64_tr_b16 v[246:247], v213 offset:0x7c00
	s_waitcnt lgkmcnt(0)
	v_mfma_f32_32x32x16_bf16 v[48:63], v[188:191], v[248:251], v[48:63]
	v_max3_f32 v252, v252, v104, v105
	v_max3_f32 v252, v252, v106, v107
	v_mfma_f32_32x32x16_bf16 v[16:31], v[176:179], v[232:235], v[16:31]
	v_max3_f32 v252, v252, v108, v109
	v_max3_f32 v252, v252, v110, v111
	ds_read_b64_tr_b16 v[232:233], v213 offset:0x4600
	ds_read_b64_tr_b16 v[234:235], v213 offset:0x4e00
	v_mfma_f32_32x32x16_bf16 v[16:31], v[180:183], v[236:239], v[16:31]
	v_mov_b32_e32 v253, v252
	s_nop 1
	ds_read_b64_tr_b16 v[236:237], v213 offset:0x5600
	ds_read_b64_tr_b16 v[238:239], v213 offset:0x5e00
	v_mfma_f32_32x32x16_bf16 v[16:31], v[184:187], v[240:243], v[16:31]
	v_permlane32_swap_b32_e32 v252, v253
	v_max_f32_e32 v253, v253, v253
	ds_read_b64_tr_b16 v[240:241], v213 offset:0x6600
	ds_read_b64_tr_b16 v[242:243], v213 offset:0x6e00
	ds_read_b64_tr_b16 v[248:249], v213 offset:0x7600
	ds_read_b64_tr_b16 v[250:251], v213 offset:0x7e00
	s_waitcnt lgkmcnt(0)
	v_mfma_f32_32x32x16_bf16 v[16:31], v[188:191], v[244:247], v[16:31]
	v_max_f32_e32 v252, v252, v252
	v_max_f32_e32 v252, v252, v253
	v_mfma_f32_32x32x16_bf16 v[0:15], v[176:179], v[232:235], v[0:15]
	v_sub_f32_e32 v253, v252, v229
	v_mul_f32_e32 v253, 0x3db504f3, v253
	v_mfma_f32_32x32x16_bf16 v[0:15], v[180:183], v[236:239], v[0:15]
	v_cmp_ge_f32_e32 vcc, s63, v253
	v_mfma_f32_32x32x16_bf16 v[0:15], v[184:187], v[240:243], v[0:15]
	v_mfma_f32_32x32x16_bf16 v[0:15], v[188:191], v[248:251], v[0:15]
	v_mov_b32_e32 v176, v252
	s_cmp_eq_u64 vcc, exec
	s_cselect_b64 s[10:11], -1, 0
	s_andn2_b64 vcc, exec, s[48:49]
	s_waitcnt lgkmcnt(0)
	s_barrier
	s_cbranch_vccnz .LBB0_823
	s_waitcnt vmcnt(0)
	s_and_b64 vcc, exec, s[6:7]
	s_waitcnt vmcnt(0)
	ds_write_b128 v199, v[160:163] offset:16384
	ds_write_b128 v215, v[164:167] offset:16384
	s_cbranch_vccnz .LBB0_822
	v_xor_b32_e32 v160, 0x80000000, v202
	ds_write_b32 v212, v160 offset:256

; __global__ void __launch_bounds__(NTHR, 2) fwd_kernel(Args args) {
	.amdhsa_kernel _Z10fwd_kernel4Args
		.amdhsa_group_segment_fixed_size 0
		.amdhsa_private_segment_fixed_size 0
		.amdhsa_kernarg_size 440
		.amdhsa_user_sgpr_count 2
		.amdhsa_user_sgpr_dispatch_ptr 0
		.amdhsa_user_sgpr_queue_ptr 0
		.amdhsa_user_sgpr_kernarg_segment_ptr 1
		.amdhsa_user_sgpr_dispatch_id 0
		.amdhsa_user_sgpr_kernarg_preload_length 0
		.amdhsa_user_sgpr_kernarg_preload_offset 0
		.amdhsa_user_sgpr_private_segment_size 0
		.amdhsa_uses_dynamic_stack 0
		.amdhsa_enable_private_segment 0
		.amdhsa_system_sgpr_workgroup_id_x 1
		.amdhsa_system_sgpr_workgroup_id_y 0
		.amdhsa_system_sgpr_workgroup_id_z 0
		.amdhsa_system_sgpr_workgroup_info 0
		.amdhsa_system_vgpr_workitem_id 2
		.amdhsa_next_free_vgpr 256
		.amdhsa_next_free_sgpr 96
		.amdhsa_accum_offset 256
		.amdhsa_reserve_vcc 1
		.amdhsa_float_round_mode_32 0
		.amdhsa_float_round_mode_16_64 0
		.amdhsa_float_denorm_mode_32 3
		.amdhsa_float_denorm_mode_16_64 3
		.amdhsa_dx10_clamp 1
		.amdhsa_ieee_mode 1
		.amdhsa_fp16_overflow 0
		.amdhsa_tg_split 0
		.amdhsa_exception_fp_ieee_invalid_op 0
		.amdhsa_exception_fp_denorm_src 0
		.amdhsa_exception_fp_ieee_div_zero 0
		.amdhsa_exception_fp_ieee_overflow 0
		.amdhsa_exception_fp_ieee_underflow 0
		.amdhsa_exception_fp_ieee_inexact 0
		.amdhsa_exception_int_div_zero 0
	.end_amdhsa_kernel

; __global__ void __launch_bounds__(NTHR, 2) fwd_kernel(Args args) {
amdhsa.kernels:
  - .agpr_count:     0
    .args:
      - .offset:         0
        .size:           184
        .value_kind:     by_value
      - .offset:         184
        .size:           4
        .value_kind:     hidden_block_count_x
      - .offset:         188
        .size:           4
        .value_kind:     hidden_block_count_y
      - .offset:         192
        .size:           4
        .value_kind:     hidden_block_count_z
      - .offset:         196
        .size:           2
        .value_kind:     hidden_group_size_x
      - .offset:         198
        .size:           2
        .value_kind:     hidden_group_size_y
      - .offset:         200
        .size:           2
        .value_kind:     hidden_group_size_z
      - .offset:         202
        .size:           2
        .value_kind:     hidden_remainder_x
      - .offset:         204
        .size:           2
        .value_kind:     hidden_remainder_y
      - .offset:         206
        .size:           2
        .value_kind:     hidden_remainder_z
      - .offset:         224
        .size:           8
        .value_kind:     hidden_global_offset_x
      - .offset:         232
        .size:           8
        .value_kind:     hidden_global_offset_y
      - .offset:         240
        .size:           8
        .value_kind:     hidden_global_offset_z
      - .offset:         248
        .size:           2
        .value_kind:     hidden_grid_dims
      - .offset:         272
        .size:           8
        .value_kind:     hidden_multigrid_sync_arg
      - .offset:         304
        .size:           4
        .value_kind:     hidden_dynamic_lds_size
    .group_segment_fixed_size: 0
    .kernarg_segment_align: 8
    .kernarg_segment_size: 440
    .language:       OpenCL C
    .language_version:
      - 2
      - 0
    .max_flat_workgroup_size: 512
    .name:           _Z10fwd_kernel4Args
    .private_segment_fixed_size: 0
    .sgpr_count:     102
    .sgpr_spill_count: 0
    .symbol:         _Z10fwd_kernel4Args.kd
    .uniform_work_group_size: 1
    .uses_dynamic_stack: false
    .vgpr_count:     256
    .vgpr_spill_count: 0
    .wavefront_size: 64
